# counted-wait repair in P0: two full vmcnt(0) drains inside the 128-load batch of the gate/up strip conversion moved behind the last load (one counted wait), on top of stack7
# speedup vs baseline: 1.0005x; 1.0005x over previous
.LBB0_17:
	s_mul_hi_i32 s6, s26, 0x2e8ba2e9
	s_load_dwordx16 s[60:75], s[0:1], 0x40
	s_lshr_b32 s7, s6, 31
	s_ashr_i32 s27, s6, 6
	s_add_i32 s27, s27, s7
	s_mul_i32 s6, s27, 0xfffffea0
	s_add_i32 s6, s26, s6
	s_mul_i32 s8, s27, 0x5800000
	s_mul_hi_i32 s7, s27, 0x5800000
	s_waitcnt lgkmcnt(0)
	s_add_u32 s28, s60, s8
	s_addc_u32 s29, s61, s7
	s_mul_i32 s7, s27, 0xffffd400
	s_add_i32 s8, s14, s7
	s_cmpk_gt_i32 s6, 0xaf
	s_cselect_b32 s6, 0xffffea00, 0
	s_cselect_b32 s9, 0x80, 0
	s_add_i32 s6, s8, s6
	s_lshl_b32 s7, s6, 1
	s_and_b32 s6, s8, 0x60
	s_or_b32 s6, s9, s6
	s_ashr_i32 s9, s8, 31
	s_lshl_b64 s[8:9], s[8:9], 2
	s_add_u32 s8, s28, s8
	s_addc_u32 s9, s29, s9
	v_lshl_add_u64 v[8:9], s[8:9], 0, v[6:7]
	v_lshl_add_u64 v[8:9], v[8:9], 0, v[2:3]
	s_mov_b32 s8, 0xb000
	v_add_co_u32_e32 v28, vcc, s8, v8
	s_mov_b32 s8, 0x16000
	s_nop 0
	v_addc_co_u32_e32 v29, vcc, 0, v9, vcc
	global_load_dword v26, v[8:9], off nt
	global_load_dword v27, v[28:29], off nt
	v_add_co_u32_e32 v28, vcc, s8, v8
	s_mov_b32 s8, 0x21000
	s_nop 0
	v_addc_co_u32_e32 v29, vcc, 0, v9, vcc
	v_add_co_u32_e32 v30, vcc, s8, v8
	s_mov_b32 s8, 0x2c0000
	s_nop 0
	v_addc_co_u32_e32 v31, vcc, 0, v9, vcc
	global_load_dword v28, v[28:29], off nt
	s_and_b32 s7, s7, 0xffffff00
	global_load_dword v29, v[30:31], off nt
	v_add_co_u32_e32 v30, vcc, s8, v8
	s_mov_b32 s8, 0x2cb000
	s_nop 0
	v_addc_co_u32_e32 v31, vcc, 0, v9, vcc
	v_add_co_u32_e32 v32, vcc, s8, v8
	s_mov_b32 s8, 0x2d6000
	s_nop 0
	v_addc_co_u32_e32 v33, vcc, 0, v9, vcc
	global_load_dword v30, v[30:31], off nt
	s_or_b32 s28, s6, s7
	global_load_dword v31, v[32:33], off nt
	v_add_co_u32_e32 v32, vcc, s8, v8
	s_mov_b32 s8, 0x2e1000
	s_nop 0
	v_addc_co_u32_e32 v33, vcc, 0, v9, vcc
	v_add_co_u32_e32 v34, vcc, s8, v8
	s_mov_b32 s8, 0x580000
	s_nop 0
	v_addc_co_u32_e32 v35, vcc, 0, v9, vcc
	global_load_dword v32, v[32:33], off nt
	global_load_dword v33, v[34:35], off nt
	v_add_co_u32_e32 v34, vcc, s8, v8
	s_mov_b32 s8, 0x58b000
	s_nop 0
	v_addc_co_u32_e32 v35, vcc, 0, v9, vcc
	v_add_co_u32_e32 v36, vcc, s8, v8
	s_mov_b32 s8, 0x596000
	s_nop 0
	v_addc_co_u32_e32 v37, vcc, 0, v9, vcc
	global_load_dword v34, v[34:35], off nt
	s_nop 0
	global_load_dword v35, v[36:37], off nt
	v_add_co_u32_e32 v36, vcc, s8, v8
	s_mov_b32 s8, 0x5a1000
	s_nop 0
	v_addc_co_u32_e32 v37, vcc, 0, v9, vcc
	v_add_co_u32_e32 v38, vcc, s8, v8
	s_mov_b32 s8, 0x840000
	s_nop 0
	v_addc_co_u32_e32 v39, vcc, 0, v9, vcc
	global_load_dword v36, v[36:37], off nt
	s_nop 0
	global_load_dword v37, v[38:39], off nt
	v_add_co_u32_e32 v38, vcc, s8, v8
	s_mov_b32 s8, 0x84b000
	s_nop 0
	v_addc_co_u32_e32 v39, vcc, 0, v9, vcc
	v_add_co_u32_e32 v40, vcc, s8, v8
	s_mov_b32 s8, 0x856000
	s_nop 0
	v_addc_co_u32_e32 v41, vcc, 0, v9, vcc
	global_load_dword v38, v[38:39], off nt
	s_nop 0
	global_load_dword v39, v[40:41], off nt
	v_add_co_u32_e32 v40, vcc, s8, v8
	s_mov_b32 s8, 0x861000
	s_nop 0
	v_addc_co_u32_e32 v41, vcc, 0, v9, vcc
	v_add_co_u32_e32 v42, vcc, s8, v8
	s_mov_b32 s8, 0xb00000
	s_nop 0
	v_addc_co_u32_e32 v43, vcc, 0, v9, vcc
	global_load_dword v40, v[40:41], off nt
	global_load_dword v41, v[42:43], off nt
	v_add_co_u32_e32 v42, vcc, s8, v8
	s_mov_b32 s8, 0xb0b000
	s_nop 0
	v_addc_co_u32_e32 v43, vcc, 0, v9, vcc
	v_add_co_u32_e32 v44, vcc, s8, v8
	s_mov_b32 s8, 0xb16000
	s_nop 0
	v_addc_co_u32_e32 v45, vcc, 0, v9, vcc
	global_load_dword v42, v[42:43], off nt
	s_nop 0
	global_load_dword v43, v[44:45], off nt
	v_add_co_u32_e32 v44, vcc, s8, v8
	s_mov_b32 s8, 0xb21000
	s_nop 0
	v_addc_co_u32_e32 v45, vcc, 0, v9, vcc
	v_add_co_u32_e32 v46, vcc, s8, v8
	s_mov_b32 s8, 0xdc0000
	s_nop 0
	v_addc_co_u32_e32 v47, vcc, 0, v9, vcc
	global_load_dword v44, v[44:45], off nt
	s_nop 0
	global_load_dword v45, v[46:47], off nt
	v_add_co_u32_e32 v46, vcc, s8, v8
	s_mov_b32 s8, 0xdcb000
	s_nop 0
	v_addc_co_u32_e32 v47, vcc, 0, v9, vcc
	v_add_co_u32_e32 v48, vcc, s8, v8
	s_mov_b32 s8, 0xdd6000
	s_nop 0
	v_addc_co_u32_e32 v49, vcc, 0, v9, vcc
	global_load_dword v46, v[46:47], off nt
	s_nop 0
	global_load_dword v47, v[48:49], off nt
	v_add_co_u32_e32 v48, vcc, s8, v8
	s_mov_b32 s8, 0xde1000
	s_nop 0
	v_addc_co_u32_e32 v49, vcc, 0, v9, vcc
	v_add_co_u32_e32 v50, vcc, s8, v8
	s_mov_b32 s8, 0x1080000
	s_nop 0
	v_addc_co_u32_e32 v51, vcc, 0, v9, vcc
	global_load_dword v48, v[48:49], off nt
	s_nop 0
	global_load_dword v49, v[50:51], off nt
	v_add_co_u32_e32 v50, vcc, s8, v8
	s_mov_b32 s8, 0x108b000
	s_nop 0
	v_addc_co_u32_e32 v51, vcc, 0, v9, vcc
	v_add_co_u32_e32 v52, vcc, s8, v8
	s_mov_b32 s8, 0x1096000
	s_nop 0
	v_addc_co_u32_e32 v53, vcc, 0, v9, vcc
	global_load_dword v50, v[50:51], off nt
	s_nop 0
	global_load_dword v51, v[52:53], off nt
	v_add_co_u32_e32 v52, vcc, s8, v8
	s_mov_b32 s8, 0x10a1000
	s_nop 0
	v_addc_co_u32_e32 v53, vcc, 0, v9, vcc
	v_add_co_u32_e32 v54, vcc, s8, v8
	s_mov_b32 s8, 0x1340000
	s_nop 0
	v_addc_co_u32_e32 v55, vcc, 0, v9, vcc
	global_load_dword v52, v[52:53], off nt
	s_nop 0
	global_load_dword v53, v[54:55], off nt
	v_add_co_u32_e32 v54, vcc, s8, v8
	s_mov_b32 s8, 0x134b000
	s_nop 0
	v_addc_co_u32_e32 v55, vcc, 0, v9, vcc
	v_add_co_u32_e32 v56, vcc, s8, v8
	s_mov_b32 s8, 0x1356000
	s_nop 0
	v_addc_co_u32_e32 v57, vcc, 0, v9, vcc
	global_load_dword v54, v[54:55], off nt
	s_nop 0
	global_load_dword v55, v[56:57], off nt
	v_add_co_u32_e32 v56, vcc, s8, v8
	s_mov_b32 s8, 0x1361000
	s_nop 0
	v_addc_co_u32_e32 v57, vcc, 0, v9, vcc
	v_add_co_u32_e32 v58, vcc, s8, v8
	s_mov_b32 s8, 0x1600000
	s_nop 0
	v_addc_co_u32_e32 v59, vcc, 0, v9, vcc
	global_load_dword v56, v[56:57], off nt
	s_nop 0
	global_load_dword v57, v[58:59], off nt
	v_add_co_u32_e32 v58, vcc, s8, v8
	s_mov_b32 s8, 0x160b000
	s_nop 0
	v_addc_co_u32_e32 v59, vcc, 0, v9, vcc
	v_add_co_u32_e32 v60, vcc, s8, v8
	s_mov_b32 s8, 0x1616000
	s_nop 0
	v_addc_co_u32_e32 v61, vcc, 0, v9, vcc
	global_load_dword v58, v[58:59], off nt
	s_nop 0
	global_load_dword v59, v[60:61], off nt
	v_add_co_u32_e32 v60, vcc, s8, v8
	s_mov_b32 s8, 0x1621000
	s_nop 0
	v_addc_co_u32_e32 v61, vcc, 0, v9, vcc
	v_add_co_u32_e32 v62, vcc, s8, v8
	s_mov_b32 s8, 0x18c0000
	s_nop 0
	v_addc_co_u32_e32 v63, vcc, 0, v9, vcc
	global_load_dword v60, v[60:61], off nt
	s_nop 0
	global_load_dword v61, v[62:63], off nt
	v_add_co_u32_e32 v62, vcc, s8, v8
	s_mov_b32 s8, 0x18cb000
	s_nop 0
	v_addc_co_u32_e32 v63, vcc, 0, v9, vcc
	v_add_co_u32_e32 v64, vcc, s8, v8
	s_mov_b32 s8, 0x18d6000
	s_nop 0
	v_addc_co_u32_e32 v65, vcc, 0, v9, vcc
	global_load_dword v62, v[62:63], off nt
	s_nop 0
	global_load_dword v63, v[64:65], off nt
	v_add_co_u32_e32 v64, vcc, s8, v8
	s_mov_b32 s8, 0x18e1000
	s_nop 0
	v_addc_co_u32_e32 v65, vcc, 0, v9, vcc
	v_add_co_u32_e32 v66, vcc, s8, v8
	s_mov_b32 s8, 0x1b80000
	s_nop 0
	v_addc_co_u32_e32 v67, vcc, 0, v9, vcc
	global_load_dword v64, v[64:65], off nt
	s_nop 0
	global_load_dword v65, v[66:67], off nt
	v_add_co_u32_e32 v66, vcc, s8, v8
	s_mov_b32 s8, 0x1b8b000
	s_nop 0
	v_addc_co_u32_e32 v67, vcc, 0, v9, vcc
	v_add_co_u32_e32 v68, vcc, s8, v8
	s_mov_b32 s8, 0x1b96000
	s_nop 0
	v_addc_co_u32_e32 v69, vcc, 0, v9, vcc
	global_load_dword v66, v[66:67], off nt
	s_nop 0
	global_load_dword v67, v[68:69], off nt
	v_add_co_u32_e32 v68, vcc, s8, v8
	s_mov_b32 s8, 0x1ba1000
	s_nop 0
	v_addc_co_u32_e32 v69, vcc, 0, v9, vcc
	v_add_co_u32_e32 v70, vcc, s8, v8
	s_mov_b32 s8, 0x1e40000
	s_nop 0
	v_addc_co_u32_e32 v71, vcc, 0, v9, vcc
	global_load_dword v68, v[68:69], off nt
	s_nop 0
	global_load_dword v69, v[70:71], off nt
	v_add_co_u32_e32 v70, vcc, s8, v8
	s_mov_b32 s8, 0x1e4b000
	s_nop 0
	v_addc_co_u32_e32 v71, vcc, 0, v9, vcc
	v_add_co_u32_e32 v72, vcc, s8, v8
	s_mov_b32 s8, 0x1e56000
	s_nop 0
	v_addc_co_u32_e32 v73, vcc, 0, v9, vcc
	global_load_dword v70, v[70:71], off nt
	s_nop 0
	global_load_dword v71, v[72:73], off nt
	v_add_co_u32_e32 v72, vcc, s8, v8
	s_mov_b32 s8, 0x1e61000
	s_nop 0
	v_addc_co_u32_e32 v73, vcc, 0, v9, vcc
	v_add_co_u32_e32 v74, vcc, s8, v8
	s_mov_b32 s8, 0x2100000
	s_nop 0
	v_addc_co_u32_e32 v75, vcc, 0, v9, vcc
	global_load_dword v72, v[72:73], off nt
	s_nop 0
	global_load_dword v73, v[74:75], off nt
	v_add_co_u32_e32 v74, vcc, s8, v8
	s_mov_b32 s8, 0x210b000
	s_nop 0
	v_addc_co_u32_e32 v75, vcc, 0, v9, vcc
	v_add_co_u32_e32 v76, vcc, s8, v8
	s_mov_b32 s8, 0x2116000
	s_nop 0
	v_addc_co_u32_e32 v77, vcc, 0, v9, vcc
	global_load_dword v74, v[74:75], off nt
	s_nop 0
	global_load_dword v75, v[76:77], off nt
	v_add_co_u32_e32 v76, vcc, s8, v8
	s_mov_b32 s8, 0x2121000
	s_nop 0
	v_addc_co_u32_e32 v77, vcc, 0, v9, vcc
	v_add_co_u32_e32 v78, vcc, s8, v8
	s_mov_b32 s8, 0x23c0000
	s_nop 0
	v_addc_co_u32_e32 v79, vcc, 0, v9, vcc
	global_load_dword v76, v[76:77], off nt
	s_nop 0
	global_load_dword v77, v[78:79], off nt
	v_add_co_u32_e32 v78, vcc, s8, v8
	s_mov_b32 s8, 0x23cb000
	s_nop 0
	v_addc_co_u32_e32 v79, vcc, 0, v9, vcc
	v_add_co_u32_e32 v80, vcc, s8, v8
	s_mov_b32 s8, 0x23d6000
	s_nop 0
	v_addc_co_u32_e32 v81, vcc, 0, v9, vcc
	global_load_dword v78, v[78:79], off nt
	s_nop 0
	global_load_dword v79, v[80:81], off nt
	v_add_co_u32_e32 v80, vcc, s8, v8
	s_mov_b32 s8, 0x23e1000
	s_nop 0
	v_addc_co_u32_e32 v81, vcc, 0, v9, vcc
	v_add_co_u32_e32 v82, vcc, s8, v8
	s_mov_b32 s8, 0x2680000
	s_nop 0
	v_addc_co_u32_e32 v83, vcc, 0, v9, vcc
	global_load_dword v80, v[80:81], off nt
	s_nop 0
	global_load_dword v81, v[82:83], off nt
	v_add_co_u32_e32 v82, vcc, s8, v8
	s_mov_b32 s8, 0x268b000
	s_nop 0
	v_addc_co_u32_e32 v83, vcc, 0, v9, vcc
	v_add_co_u32_e32 v84, vcc, s8, v8
	s_mov_b32 s8, 0x2696000
	s_nop 0
	v_addc_co_u32_e32 v85, vcc, 0, v9, vcc
	global_load_dword v82, v[82:83], off nt
	s_nop 0
	global_load_dword v83, v[84:85], off nt
	v_add_co_u32_e32 v84, vcc, s8, v8
	s_mov_b32 s8, 0x26a1000
	s_nop 0
	v_addc_co_u32_e32 v85, vcc, 0, v9, vcc
	v_add_co_u32_e32 v86, vcc, s8, v8
	s_mov_b32 s8, 0x2940000
	s_nop 0
	v_addc_co_u32_e32 v87, vcc, 0, v9, vcc
	global_load_dword v84, v[84:85], off nt
	s_nop 0
	global_load_dword v85, v[86:87], off nt
	v_add_co_u32_e32 v86, vcc, s8, v8
	s_mov_b32 s8, 0x294b000
	s_nop 0
	v_addc_co_u32_e32 v87, vcc, 0, v9, vcc
	v_add_co_u32_e32 v88, vcc, s8, v8
	s_mov_b32 s8, 0x2956000
	s_nop 0
	v_addc_co_u32_e32 v89, vcc, 0, v9, vcc
	global_load_dword v86, v[86:87], off nt
	s_nop 0
	global_load_dword v87, v[88:89], off nt
	v_add_co_u32_e32 v88, vcc, s8, v8
	s_mov_b32 s8, 0x2961000
	s_nop 0
	v_addc_co_u32_e32 v89, vcc, 0, v9, vcc
	v_add_co_u32_e32 v90, vcc, s8, v8
	s_mov_b32 s8, 0x2c00000
	s_nop 0
	v_addc_co_u32_e32 v91, vcc, 0, v9, vcc
	global_load_dword v88, v[88:89], off nt
	s_nop 0
	global_load_dword v89, v[90:91], off nt
	v_add_co_u32_e32 v90, vcc, s8, v8
	s_mov_b32 s8, 0x2c0b000
	s_nop 0
	v_addc_co_u32_e32 v91, vcc, 0, v9, vcc
	v_add_co_u32_e32 v92, vcc, s8, v8
	s_mov_b32 s8, 0x2c16000
	s_nop 0
	v_addc_co_u32_e32 v93, vcc, 0, v9, vcc
	global_load_dword v90, v[90:91], off nt
	s_nop 0
	global_load_dword v91, v[92:93], off nt
	v_add_co_u32_e32 v92, vcc, s8, v8
	s_mov_b32 s8, 0x2c21000
	s_nop 0
	v_addc_co_u32_e32 v93, vcc, 0, v9, vcc
	v_add_co_u32_e32 v94, vcc, s8, v8
	s_mov_b32 s8, 0x2ec0000
	s_nop 0
	v_addc_co_u32_e32 v95, vcc, 0, v9, vcc
	global_load_dword v92, v[92:93], off nt
	s_nop 0
	global_load_dword v93, v[94:95], off nt
	v_add_co_u32_e32 v94, vcc, s8, v8
	s_mov_b32 s8, 0x2ecb000
	s_nop 0
	v_addc_co_u32_e32 v95, vcc, 0, v9, vcc
	v_add_co_u32_e32 v96, vcc, s8, v8
	s_mov_b32 s8, 0x2ed6000
	s_nop 0
	v_addc_co_u32_e32 v97, vcc, 0, v9, vcc
	global_load_dword v94, v[94:95], off nt
	s_nop 0
	global_load_dword v95, v[96:97], off nt
	v_add_co_u32_e32 v96, vcc, s8, v8
	s_mov_b32 s8, 0x2ee1000
	s_nop 0
	v_addc_co_u32_e32 v97, vcc, 0, v9, vcc
	v_add_co_u32_e32 v98, vcc, s8, v8
	s_mov_b32 s8, 0x3180000
	s_nop 0
	v_addc_co_u32_e32 v99, vcc, 0, v9, vcc
	global_load_dword v96, v[96:97], off nt
	s_nop 0
	global_load_dword v97, v[98:99], off nt
	v_add_co_u32_e32 v98, vcc, s8, v8
	s_mov_b32 s8, 0x318b000
	s_nop 0
	v_addc_co_u32_e32 v99, vcc, 0, v9, vcc
	v_add_co_u32_e32 v100, vcc, s8, v8
	s_mov_b32 s8, 0x3196000
	s_nop 0
	v_addc_co_u32_e32 v101, vcc, 0, v9, vcc
	global_load_dword v98, v[98:99], off nt
	s_nop 0
	global_load_dword v99, v[100:101], off nt
	v_add_co_u32_e32 v100, vcc, s8, v8
	s_mov_b32 s8, 0x31a1000
	s_nop 0
	v_addc_co_u32_e32 v101, vcc, 0, v9, vcc
	v_add_co_u32_e32 v102, vcc, s8, v8
	s_mov_b32 s8, 0x3440000
	s_nop 0
	v_addc_co_u32_e32 v103, vcc, 0, v9, vcc
	global_load_dword v100, v[100:101], off nt
	s_nop 0
	global_load_dword v101, v[102:103], off nt
	v_add_co_u32_e32 v102, vcc, s8, v8
	s_mov_b32 s8, 0x344b000
	s_nop 0
	v_addc_co_u32_e32 v103, vcc, 0, v9, vcc
	v_add_co_u32_e32 v104, vcc, s8, v8
	s_mov_b32 s8, 0x3456000
	s_nop 0
	v_addc_co_u32_e32 v105, vcc, 0, v9, vcc
	global_load_dword v102, v[102:103], off nt
	s_nop 0
	global_load_dword v103, v[104:105], off nt
	v_add_co_u32_e32 v104, vcc, s8, v8
	s_mov_b32 s8, 0x3461000
	s_nop 0
	v_addc_co_u32_e32 v105, vcc, 0, v9, vcc
	v_add_co_u32_e32 v106, vcc, s8, v8
	s_mov_b32 s8, 0x3700000
	s_nop 0
	v_addc_co_u32_e32 v107, vcc, 0, v9, vcc
	global_load_dword v104, v[104:105], off nt
	s_nop 0
	global_load_dword v105, v[106:107], off nt
	v_add_co_u32_e32 v106, vcc, s8, v8
	s_mov_b32 s8, 0x370b000
	s_nop 0
	v_addc_co_u32_e32 v107, vcc, 0, v9, vcc
	v_add_co_u32_e32 v108, vcc, s8, v8
	s_mov_b32 s8, 0x3716000
	s_nop 0
	v_addc_co_u32_e32 v109, vcc, 0, v9, vcc
	global_load_dword v106, v[106:107], off nt
	s_nop 0
	global_load_dword v107, v[108:109], off nt
	v_add_co_u32_e32 v108, vcc, s8, v8
	s_mov_b32 s8, 0x3721000
	s_nop 0
	v_addc_co_u32_e32 v109, vcc, 0, v9, vcc
	v_add_co_u32_e32 v110, vcc, s8, v8
	s_mov_b32 s8, 0x39c0000
	s_nop 0
	v_addc_co_u32_e32 v111, vcc, 0, v9, vcc
	global_load_dword v108, v[108:109], off nt
	s_nop 0
	global_load_dword v109, v[110:111], off nt
	v_add_co_u32_e32 v110, vcc, s8, v8
	s_mov_b32 s8, 0x39cb000
	s_nop 0
	v_addc_co_u32_e32 v111, vcc, 0, v9, vcc
	v_add_co_u32_e32 v112, vcc, s8, v8
	s_mov_b32 s8, 0x39d6000
	s_nop 0
	v_addc_co_u32_e32 v113, vcc, 0, v9, vcc
	global_load_dword v110, v[110:111], off nt
	s_nop 0
	global_load_dword v111, v[112:113], off nt
	v_add_co_u32_e32 v112, vcc, s8, v8
	s_mov_b32 s8, 0x39e1000
	s_nop 0
	v_addc_co_u32_e32 v113, vcc, 0, v9, vcc
	v_add_co_u32_e32 v114, vcc, s8, v8
	s_mov_b32 s8, 0x3c80000
	s_nop 0
	v_addc_co_u32_e32 v115, vcc, 0, v9, vcc
	global_load_dword v112, v[112:113], off nt
	s_nop 0
	global_load_dword v113, v[114:115], off nt
	v_add_co_u32_e32 v114, vcc, s8, v8
	s_mov_b32 s8, 0x3c8b000
	s_nop 0
	v_addc_co_u32_e32 v115, vcc, 0, v9, vcc
	v_add_co_u32_e32 v116, vcc, s8, v8
	s_mov_b32 s8, 0x3c96000
	s_nop 0
	v_addc_co_u32_e32 v117, vcc, 0, v9, vcc
	global_load_dword v114, v[114:115], off nt
	s_nop 0
	global_load_dword v115, v[116:117], off nt
	v_add_co_u32_e32 v116, vcc, s8, v8
	s_mov_b32 s8, 0x3ca1000
	s_nop 0
	v_addc_co_u32_e32 v117, vcc, 0, v9, vcc
	v_add_co_u32_e32 v118, vcc, s8, v8
	s_mov_b32 s8, 0x3f40000
	s_nop 0
	v_addc_co_u32_e32 v119, vcc, 0, v9, vcc
	global_load_dword v116, v[116:117], off nt
	s_nop 0
	global_load_dword v117, v[118:119], off nt
	v_add_co_u32_e32 v118, vcc, s8, v8
	s_mov_b32 s8, 0x3f4b000
	s_nop 0
	v_addc_co_u32_e32 v119, vcc, 0, v9, vcc
	v_add_co_u32_e32 v120, vcc, s8, v8
	s_mov_b32 s8, 0x3f56000
	s_nop 0
	v_addc_co_u32_e32 v121, vcc, 0, v9, vcc
	global_load_dword v118, v[118:119], off nt
	s_nop 0
	global_load_dword v119, v[120:121], off nt
	v_add_co_u32_e32 v120, vcc, s8, v8
	s_mov_b32 s8, 0x3f61000
	s_nop 0
	v_addc_co_u32_e32 v121, vcc, 0, v9, vcc
	v_add_co_u32_e32 v122, vcc, s8, v8
	s_mov_b32 s8, 0x4200000
	s_nop 0
	v_addc_co_u32_e32 v123, vcc, 0, v9, vcc
	global_load_dword v120, v[120:121], off nt
	s_nop 0
	global_load_dword v121, v[122:123], off nt
	v_add_co_u32_e32 v122, vcc, s8, v8
	s_mov_b32 s8, 0x420b000
	s_nop 0
	v_addc_co_u32_e32 v123, vcc, 0, v9, vcc
	v_add_co_u32_e32 v124, vcc, s8, v8
	s_mov_b32 s8, 0x4216000
	s_nop 0
	v_addc_co_u32_e32 v125, vcc, 0, v9, vcc
	global_load_dword v122, v[122:123], off nt
	s_nop 0
	global_load_dword v123, v[124:125], off nt
	v_add_co_u32_e32 v124, vcc, s8, v8
	s_mov_b32 s8, 0x4221000
	s_nop 0
	v_addc_co_u32_e32 v125, vcc, 0, v9, vcc
	v_add_co_u32_e32 v126, vcc, s8, v8
	s_mov_b32 s8, 0x44c0000
	s_nop 0
	v_addc_co_u32_e32 v127, vcc, 0, v9, vcc
	global_load_dword v124, v[124:125], off nt
	s_nop 0
	global_load_dword v125, v[126:127], off nt
	v_add_co_u32_e32 v126, vcc, s8, v8
	s_mov_b32 s8, 0x44cb000
	s_nop 0
	v_addc_co_u32_e32 v127, vcc, 0, v9, vcc
	v_add_co_u32_e32 v128, vcc, s8, v8
	s_mov_b32 s8, 0x44d6000
	s_nop 0
	v_addc_co_u32_e32 v129, vcc, 0, v9, vcc
	global_load_dword v126, v[126:127], off nt
	s_nop 0
	global_load_dword v127, v[128:129], off nt
	v_add_co_u32_e32 v128, vcc, s8, v8
	s_mov_b32 s8, 0x44e1000
	s_nop 0
	v_addc_co_u32_e32 v129, vcc, 0, v9, vcc
	v_add_co_u32_e32 v130, vcc, s8, v8
	s_mov_b32 s8, 0x4780000
	s_nop 0
	v_addc_co_u32_e32 v131, vcc, 0, v9, vcc
	global_load_dword v128, v[128:129], off nt
	s_nop 0
	global_load_dword v129, v[130:131], off nt
	v_add_co_u32_e32 v130, vcc, s8, v8
	s_mov_b32 s8, 0x478b000
	s_nop 0
	v_addc_co_u32_e32 v131, vcc, 0, v9, vcc
	v_add_co_u32_e32 v132, vcc, s8, v8
	s_mov_b32 s8, 0x4796000
	s_nop 0
	v_addc_co_u32_e32 v133, vcc, 0, v9, vcc
	global_load_dword v130, v[130:131], off nt
	s_nop 0
	global_load_dword v131, v[132:133], off nt
	v_add_co_u32_e32 v132, vcc, s8, v8
	s_mov_b32 s8, 0x47a1000
	s_nop 0
	v_addc_co_u32_e32 v133, vcc, 0, v9, vcc
	v_add_co_u32_e32 v134, vcc, s8, v8
	s_mov_b32 s8, 0x4a40000
	s_nop 0
	v_addc_co_u32_e32 v135, vcc, 0, v9, vcc
	global_load_dword v132, v[132:133], off nt
	s_nop 0
	global_load_dword v133, v[134:135], off nt
	v_add_co_u32_e32 v134, vcc, s8, v8
	s_mov_b32 s8, 0x4a4b000
	s_nop 0
	v_addc_co_u32_e32 v135, vcc, 0, v9, vcc
	v_add_co_u32_e32 v136, vcc, s8, v8
	s_mov_b32 s8, 0x4a56000
	s_nop 0
	v_addc_co_u32_e32 v137, vcc, 0, v9, vcc
	global_load_dword v134, v[134:135], off nt
	s_nop 0
	global_load_dword v135, v[136:137], off nt
	v_add_co_u32_e32 v136, vcc, s8, v8
	s_mov_b32 s8, 0x4a61000
	s_nop 0
	v_addc_co_u32_e32 v137, vcc, 0, v9, vcc
	v_add_co_u32_e32 v138, vcc, s8, v8
	s_mov_b32 s8, 0x4d00000
	s_nop 0
	v_addc_co_u32_e32 v139, vcc, 0, v9, vcc
	global_load_dword v136, v[136:137], off nt
	s_nop 0
	global_load_dword v137, v[138:139], off nt
	v_add_co_u32_e32 v138, vcc, s8, v8
	s_mov_b32 s8, 0x4d0b000
	s_nop 0
	v_addc_co_u32_e32 v139, vcc, 0, v9, vcc
	v_add_co_u32_e32 v140, vcc, s8, v8
	s_mov_b32 s8, 0x4d16000
	s_nop 0
	v_addc_co_u32_e32 v141, vcc, 0, v9, vcc
	global_load_dword v138, v[138:139], off nt
	s_nop 0
	global_load_dword v139, v[140:141], off nt
	v_add_co_u32_e32 v140, vcc, s8, v8
	s_mov_b32 s8, 0x4d21000
	s_nop 0
	v_addc_co_u32_e32 v141, vcc, 0, v9, vcc
	v_add_co_u32_e32 v142, vcc, s8, v8
	s_mov_b32 s8, 0x4fc0000
	s_nop 0
	v_addc_co_u32_e32 v143, vcc, 0, v9, vcc
	global_load_dword v140, v[140:141], off nt
	s_nop 0
	global_load_dword v141, v[142:143], off nt
	v_add_co_u32_e32 v142, vcc, s8, v8
	s_mov_b32 s8, 0x4fcb000
	s_nop 0
	v_addc_co_u32_e32 v143, vcc, 0, v9, vcc
	v_add_co_u32_e32 v144, vcc, s8, v8
	s_mov_b32 s8, 0x4fd6000
	s_nop 0
	v_addc_co_u32_e32 v145, vcc, 0, v9, vcc
	global_load_dword v142, v[142:143], off nt
	s_nop 0
	global_load_dword v143, v[144:145], off nt
	v_add_co_u32_e32 v144, vcc, s8, v8
	s_mov_b32 s8, 0x4fe1000
	s_nop 0
	v_addc_co_u32_e32 v145, vcc, 0, v9, vcc
	v_add_co_u32_e32 v146, vcc, s8, v8
	s_mov_b32 s8, 0x5280000
	s_nop 0
	v_addc_co_u32_e32 v147, vcc, 0, v9, vcc
	global_load_dword v144, v[144:145], off nt
	s_nop 0
	global_load_dword v145, v[146:147], off nt
	v_add_co_u32_e32 v146, vcc, s8, v8
	s_mov_b32 s8, 0x528b000
	s_nop 0
	v_addc_co_u32_e32 v147, vcc, 0, v9, vcc
	v_add_co_u32_e32 v148, vcc, s8, v8
	global_load_dword v146, v[146:147], off nt
	s_nop 0
	v_addc_co_u32_e32 v149, vcc, 0, v9, vcc
	global_load_dword v147, v[148:149], off nt
	v_add_co_u32_e32 v148, vcc, s16, v8
	s_nop 1
	v_addc_co_u32_e32 v149, vcc, 0, v9, vcc
	v_add_co_u32_e32 v150, vcc, s17, v8
	global_load_dword v148, v[148:149], off nt
	s_nop 0
	v_addc_co_u32_e32 v151, vcc, 0, v9, vcc
	global_load_dword v149, v[150:151], off nt
	v_add_co_u32_e32 v150, vcc, s18, v8
	s_nop 1
	v_addc_co_u32_e32 v151, vcc, 0, v9, vcc
	v_add_co_u32_e32 v152, vcc, s19, v8
	global_load_dword v150, v[150:151], off nt
	s_nop 0
	v_addc_co_u32_e32 v153, vcc, 0, v9, vcc
	global_load_dword v151, v[152:153], off nt
	v_add_co_u32_e32 v152, vcc, s20, v8
	s_nop 1
	v_addc_co_u32_e32 v153, vcc, 0, v9, vcc
	v_add_co_u32_e32 v8, vcc, s21, v8
	global_load_dword v152, v[152:153], off nt
	s_nop 0
	v_addc_co_u32_e32 v9, vcc, 0, v9, vcc
	global_load_dword v8, v[8:9], off nt
	s_waitcnt vmcnt(62)
	v_max_f32_e64 v154, |v32|, |v32|
	v_max_f32_e64 v155, |v40|, |v40|
	v_max_f32_e64 v9, |v29|, |v29|
	v_max_f32_e64 v153, |v28|, |v28|
	v_max_f32_e32 v9, v153, v9
	v_max_f32_e64 v153, |v33|, |v33|
	v_max_f32_e32 v153, v154, v153
	v_max3_f32 v9, |v26|, |v27|, v9
	v_max3_f32 v153, |v30|, |v31|, v153
	v_max3_f32 v9, v9, 0, v153
	v_max_f32_e64 v153, |v37|, |v37|
	v_max_f32_e64 v154, |v36|, |v36|
	v_max_f32_e32 v153, v154, v153
	s_waitcnt vmcnt(62)
	v_max_f32_e64 v154, |v41|, |v41|
	v_max_f32_e32 v154, v155, v154
	v_max3_f32 v153, |v34|, |v35|, v153
	v_max3_f32 v154, |v38|, |v39|, v154
	v_max3_f32 v9, v9, v153, v154
	v_max_f32_e64 v153, |v45|, |v45|
	v_max_f32_e64 v154, |v44|, |v44|
	v_max_f32_e32 v153, v154, v153
	v_max_f32_e64 v154, |v49|, |v49|
	v_max_f32_e64 v155, |v48|, |v48|
	v_max_f32_e32 v154, v155, v154
	v_max3_f32 v153, |v42|, |v43|, v153
	v_max3_f32 v154, |v46|, |v47|, v154
	v_max3_f32 v9, v9, v153, v154
	v_max_f32_e64 v153, |v53|, |v53|
	v_max_f32_e64 v154, |v52|, |v52|
	v_max_f32_e32 v153, v154, v153
	v_max_f32_e64 v154, |v57|, |v57|
	v_max_f32_e64 v155, |v56|, |v56|
	v_max_f32_e32 v154, v155, v154
	v_max3_f32 v153, |v50|, |v51|, v153
	v_max3_f32 v154, |v54|, |v55|, v154
	v_max3_f32 v9, v9, v153, v154
	v_max_f32_e64 v153, |v61|, |v61|
	v_max_f32_e64 v154, |v60|, |v60|
	v_max_f32_e32 v153, v154, v153
	v_max_f32_e64 v154, |v65|, |v65|
	v_max_f32_e64 v155, |v64|, |v64|
	v_max_f32_e32 v154, v155, v154
	v_max3_f32 v153, |v58|, |v59|, v153
	v_max3_f32 v154, |v62|, |v63|, v154
	v_max3_f32 v9, v9, v153, v154
	v_max_f32_e64 v153, |v69|, |v69|
	v_max_f32_e64 v154, |v68|, |v68|
	v_max_f32_e32 v153, v154, v153
	v_max_f32_e64 v154, |v73|, |v73|
	v_max_f32_e64 v155, |v72|, |v72|
	v_max_f32_e32 v154, v155, v154
	v_max3_f32 v153, |v66|, |v67|, v153
	v_max3_f32 v154, |v70|, |v71|, v154
	v_max3_f32 v9, v9, v153, v154
	v_max_f32_e64 v153, |v77|, |v77|
	v_max_f32_e64 v154, |v76|, |v76|
	v_max_f32_e32 v153, v154, v153
	v_max_f32_e64 v154, |v81|, |v81|
	v_max_f32_e64 v155, |v80|, |v80|
	v_max_f32_e32 v154, v155, v154
	v_max3_f32 v153, |v74|, |v75|, v153
	v_max3_f32 v154, |v78|, |v79|, v154
	v_max3_f32 v9, v9, v153, v154
	v_max_f32_e64 v153, |v85|, |v85|
	v_max_f32_e64 v154, |v84|, |v84|
	v_max_f32_e32 v153, v154, v153
	v_max_f32_e64 v154, |v89|, |v89|
	v_max_f32_e64 v155, |v88|, |v88|
	v_max_f32_e32 v154, v155, v154
	v_max3_f32 v153, |v82|, |v83|, v153
	v_max3_f32 v154, |v86|, |v87|, v154
	v_max3_f32 v9, v9, v153, v154
	s_waitcnt vmcnt(60)
	v_max_f32_e64 v153, |v93|, |v93|
	v_max_f32_e64 v154, |v92|, |v92|
	v_max_f32_e32 v153, v154, v153
	s_waitcnt vmcnt(56)
	v_max_f32_e64 v154, |v97|, |v97|
	v_max_f32_e64 v155, |v96|, |v96|
	v_max_f32_e32 v154, v155, v154
	v_max3_f32 v153, |v90|, |v91|, v153
	v_max3_f32 v154, |v94|, |v95|, v154
	v_max3_f32 v9, v9, v153, v154
	s_waitcnt vmcnt(52)
	v_max_f32_e64 v153, |v101|, |v101|
	v_max_f32_e64 v154, |v100|, |v100|
	v_max_f32_e32 v153, v154, v153
	s_waitcnt vmcnt(48)
	v_max_f32_e64 v154, |v105|, |v105|
	v_max_f32_e64 v155, |v104|, |v104|
	v_max_f32_e32 v154, v155, v154
	v_max3_f32 v153, |v98|, |v99|, v153
	v_max3_f32 v154, |v102|, |v103|, v154
	v_max3_f32 v9, v9, v153, v154
	s_waitcnt vmcnt(44)
	v_max_f32_e64 v153, |v109|, |v109|
	v_max_f32_e64 v154, |v108|, |v108|
	v_max_f32_e32 v153, v154, v153
	s_waitcnt vmcnt(40)
	v_max_f32_e64 v154, |v113|, |v113|
	v_max_f32_e64 v155, |v112|, |v112|
	v_max_f32_e32 v154, v155, v154
	v_max3_f32 v153, |v106|, |v107|, v153
	v_max3_f32 v154, |v110|, |v111|, v154
	v_max3_f32 v9, v9, v153, v154
	s_waitcnt vmcnt(36)
	v_max_f32_e64 v153, |v117|, |v117|
	v_max_f32_e64 v154, |v116|, |v116|
	v_max_f32_e32 v153, v154, v153
	s_waitcnt vmcnt(32)
	v_max_f32_e64 v154, |v121|, |v121|
	v_max_f32_e64 v155, |v120|, |v120|
	v_max_f32_e32 v154, v155, v154
	v_max3_f32 v153, |v114|, |v115|, v153
	v_max3_f32 v154, |v118|, |v119|, v154
	v_max3_f32 v9, v9, v153, v154
	s_waitcnt vmcnt(28)
	v_max_f32_e64 v153, |v125|, |v125|
	v_max_f32_e64 v154, |v124|, |v124|
	v_max_f32_e32 v153, v154, v153
	s_waitcnt vmcnt(24)
	v_max_f32_e64 v154, |v129|, |v129|
	v_max_f32_e64 v155, |v128|, |v128|
	v_max_f32_e32 v154, v155, v154
	v_max3_f32 v153, |v122|, |v123|, v153
	v_max3_f32 v154, |v126|, |v127|, v154
	v_max3_f32 v9, v9, v153, v154
	s_waitcnt vmcnt(20)
	v_max_f32_e64 v153, |v133|, |v133|
	v_max_f32_e64 v154, |v132|, |v132|
	v_max_f32_e32 v153, v154, v153
	s_waitcnt vmcnt(16)
	v_max_f32_e64 v154, |v137|, |v137|
	v_max_f32_e64 v155, |v136|, |v136|
	v_max_f32_e32 v154, v155, v154
	v_max3_f32 v153, |v130|, |v131|, v153
	v_max3_f32 v154, |v134|, |v135|, v154
	v_max3_f32 v9, v9, v153, v154
	s_waitcnt vmcnt(12)
	v_max_f32_e64 v153, |v141|, |v141|
	v_max_f32_e64 v154, |v140|, |v140|
	v_max_f32_e32 v153, v154, v153
	s_waitcnt vmcnt(8)
	v_max_f32_e64 v154, |v145|, |v145|
	v_max_f32_e64 v155, |v144|, |v144|
	v_max_f32_e32 v154, v155, v154
	v_max3_f32 v153, |v138|, |v139|, v153
	v_max3_f32 v154, |v142|, |v143|, v154
	v_max3_f32 v9, v9, v153, v154
	s_waitcnt vmcnt(4)
	v_max_f32_e64 v153, |v149|, |v149|
	v_max_f32_e64 v154, |v148|, |v148|
	v_max_f32_e32 v153, v154, v153
	s_waitcnt vmcnt(0)
	v_max_f32_e64 v154, |v8|, |v8|
	v_max_f32_e64 v155, |v152|, |v152|
	v_max_f32_e32 v154, v155, v154
	v_max3_f32 v153, |v146|, |v147|, v153
	v_max3_f32 v154, |v150|, |v151|, v154
	v_max3_f32 v9, v9, v153, v154
	ds_write_b32 v1, v9
	s_waitcnt lgkmcnt(0)
	s_barrier
	ds_read2_b32 v[154:155], v10 offset1:32
	s_waitcnt lgkmcnt(0)
	v_max3_f32 v9, v154, 0, v155
	ds_read2_b32 v[154:155], v10 offset0:64 offset1:96
	s_waitcnt lgkmcnt(0)
	v_max3_f32 v9, v9, v154, v155
	ds_read2_b32 v[154:155], v10 offset0:128 offset1:160
	s_waitcnt lgkmcnt(0)
	v_max3_f32 v9, v9, v154, v155
	ds_read2_b32 v[154:155], v10 offset0:192 offset1:224
	s_waitcnt lgkmcnt(0)
	v_max3_f32 v9, v9, v154, v155
	ds_read2_b32 v[154:155], v25 offset1:32
	s_waitcnt lgkmcnt(0)
	v_max3_f32 v9, v9, v154, v155
	ds_read2_b32 v[154:155], v25 offset0:64 offset1:96
	s_waitcnt lgkmcnt(0)
	v_max3_f32 v9, v9, v154, v155
	ds_read2_b32 v[154:155], v25 offset0:128 offset1:160
	s_waitcnt lgkmcnt(0)
	v_max3_f32 v9, v9, v154, v155
	ds_read2_b32 v[154:155], v25 offset0:192 offset1:224
	s_waitcnt lgkmcnt(0)
	v_max3_f32 v9, v9, v154, v155
	v_cmp_lt_f32_e64 s[6:7], 0, v9
	s_and_saveexec_b64 s[8:9], s[4:5]
	s_cbranch_execz .LBB0_16
	s_mul_i32 s30, s27, 0xb000
	s_mul_hi_i32 s29, s27, 0xb000
	s_add_u32 s30, s12, s30
	v_or_b32_e32 v154, s28, v0
	v_mul_f32_e32 v153, 0x3c010204, v9
	s_addc_u32 s31, s13, s29
	v_ashrrev_i32_e32 v155, 31, v154
	v_cndmask_b32_e64 v153, 1.0, v153, s[6:7]
	v_lshl_add_u64 v[154:155], v[154:155], 2, s[30:31]
	global_store_dword v[154:155], v153, off
	s_branch .LBB0_16
